# stack12 + GEMM phase entry: all 14 staging LDS-DMA loads of K-tiles 0/1 issued back to back (wait vmcnt(8)+barrier moved behind the second batch)
# baseline (speedup 1.0000x reference)
; #define PG8_STAGE(bufoff, gbase, voff) do { _Pragma("unroll") for (int _i = 0; _i < 2; ++_i) \
;         __builtin_amdgcn_global_load_lds((const unsigned*)((const char*)(gbase) + (voff)[_i]), (PG8_LAS unsigned*)(lds + (bufoff) + ldsw + _i * 8192), 16, 0, 0); } while (0)
; #define PG8_WAIT_V(n) asm volatile("s_waitcnt vmcnt(" #n ")" ::: "memory")
; #define PG8_BAR __builtin_amdgcn_s_barrier()
; template <class Epi, class Sched, bool ALIGN_EPI = false, bool SP2 = false>
; __device__ __forceinline__ void gemm_phase(PG8_LAS unsigned char* lds, const Gemm g, const Sched& S, const Epi& E, int wid_in) {
;     ...
;         PG8_STAGE(PG8_SB(0, 0), cB, voffB); PG8_STAGE(PG8_SB(0, 1), cB + hstep, voffB); PG8_STAGE(PG8_SA(0, 0), cA, voffA); PG8_STAGE(PG8_SA(0, 1), cA + hstep, voffA);
;         if (wr == 1) PG8_BAR;
;         PG8_WAIT_V(2); PG8_BAR;
;         PG8_STAGE(PG8_SB(1, 0), cB + kstep, voffB); PG8_STAGE(PG8_SA(1, 0), cA + kstep, voffA); PG8_STAGE(PG8_SB(1, 1), cB + hstep + kstep, voffB);
;         PG8_WAIT_V(6); PG8_BAR;
.LBB0_264:
	s_add_u32 s8, s8, 0x23000000
	v_and_b32_e32 v18, 48, v16
	v_lshlrev_b32_e32 v20, 6, v16
	s_movk_i32 s11, 0x3c0
	s_addc_u32 s9, s9, 0
	v_and_or_b32 v18, v20, s11, v18
	s_lshl_b32 s11, s47, 5
	v_ashrrev_i32_e32 v17, 6, v16
	s_and_b32 s48, s11, 0x60
	s_add_i32 m0, s13, 0x18000
	v_lshl_add_u64 v[8:9], v[8:9], 0, s[94:95]
	s_lshl_b32 s39, s14, 6
	v_lshlrev_b32_e32 v19, 10, v17
	s_lshr_b32 s11, s48, 3
	global_load_lds_dwordx4 v[8:9], off
	v_lshl_add_u64 v[6:7], v[6:7], 0, s[94:95]
	s_add_i32 m0, s13, 0x1a000
	s_add_i32 s52, s13, 0x8000
	s_add_i32 s53, s13, 0xa000
	v_lshl_add_u32 v19, s14, 13, v19
	global_load_lds_dwordx4 v[6:7], off
	v_lshl_add_u64 v[2:3], v[2:3], 0, s[94:95]
	s_mov_b32 m0, s52
	s_add_u32 s14, s28, 0x80080
	global_load_lds_dwordx4 v[2:3], off
	v_lshl_add_u64 v[2:3], v[4:5], 0, s[94:95]
	s_mov_b32 m0, s53
	s_addc_u32 s15, s29, 0
	global_load_lds_dwordx4 v[2:3], off
	s_add_i32 m0, s13, 0x1c000
	v_lshl_add_u64 v[2:3], s[14:15], 0, v[0:1]
	global_load_lds_dwordx4 v[2:3], off
	v_lshl_add_u64 v[2:3], s[14:15], 0, v[134:135]
	s_add_i32 m0, s13, 0x1e000
	v_lshlrev_b32_e32 v16, 2, v16
	global_load_lds_dwordx4 v[2:3], off
	s_waitcnt vmcnt(8)
	s_barrier
	v_lshlrev_b32_e32 v2, 15, v13
	v_and_b32_e32 v2, 0xffff0000, v2
	v_lshl_add_u32 v2, v14, 12, v2
	v_and_b32_e32 v3, 1, v13
	v_lshl_or_b32 v2, v3, 6, v2
	v_lshl_add_u32 v136, v15, 1, v2
	v_lshlrev_b32_e32 v2, 15, v10
	v_and_b32_e32 v2, 0xffff0000, v2
	v_and_b32_e32 v16, 32, v16
	s_waitcnt vmcnt(6)
	v_lshl_add_u32 v2, v11, 12, v2
	v_and_b32_e32 v3, 1, v10
	v_bitop3_b32 v19, v18, v19, v16 bitop3:0xde
	v_add_lshl_u32 v17, s11, v17, 10
	s_cmp_lt_u32 s47, 4
	v_lshl_or_b32 v2, v3, 6, v2
	v_bitop3_b32 v140, v17, v18, v16 bitop3:0xf6
	s_cselect_b64 s[14:15], -1, 0
	v_mov_b32_e32 v137, v1
	v_lshl_add_u32 v138, v12, 1, v2
	v_mov_b32_e32 v139, v1
	s_mov_b32 s61, 0
	v_add_u32_e32 v141, 0, v19
	s_barrier
	s_branch .LBB0_267

; #define PG8_STAGE(bufoff, gbase, voff) do { _Pragma("unroll") for (int _i = 0; _i < 2; ++_i) \
;         __builtin_amdgcn_global_load_lds((const unsigned*)((const char*)(gbase) + (voff)[_i]), (PG8_LAS unsigned*)(lds + (bufoff) + ldsw + _i * 8192), 16, 0, 0); } while (0)
; #define PG8_WAIT_V(n) asm volatile("s_waitcnt vmcnt(" #n ")" ::: "memory")
; #define PG8_BAR __builtin_amdgcn_s_barrier()
; template <class Epi, class Sched, bool ALIGN_EPI = false, bool SP2 = false>
; __device__ __forceinline__ void gemm_phase(PG8_LAS unsigned char* lds, const Gemm g, const Sched& S, const Epi& E, int wid_in) {
;     ...
;         PG8_STAGE(PG8_SB(0, 0), cB, voffB); PG8_STAGE(PG8_SB(0, 1), cB + hstep, voffB); PG8_STAGE(PG8_SA(0, 0), cA, voffA); PG8_STAGE(PG8_SA(0, 1), cA + hstep, voffA);
;         if (wr == 1) PG8_BAR;
;         PG8_WAIT_V(2); PG8_BAR;
;         PG8_STAGE(PG8_SB(1, 0), cB + kstep, voffB); PG8_STAGE(PG8_SA(1, 0), cA + kstep, voffA); PG8_STAGE(PG8_SB(1, 1), cB + hstep + kstep, voffB);
;         PG8_WAIT_V(6); PG8_BAR;
.LBB0_834:
	s_add_u32 s8, s12, 0x3d5a0000
	s_addc_u32 s9, s13, 0
	s_add_u32 s10, s12, 0x23003200
	s_addc_u32 s11, s13, 0
	v_ashrrev_i32_e32 v17, 6, v16
	s_add_u32 s48, s12, 0x43ba0000
	v_lshlrev_b32_e32 v19, 10, v17
	s_addc_u32 s80, s13, 0
	s_lshl_b32 s61, s0, 6
	v_and_b32_e32 v18, 48, v16
	v_lshl_add_u32 v19, s0, 13, v19
	v_lshlrev_b32_e32 v20, 6, v16
	s_movk_i32 s0, 0x3c0
	v_and_or_b32 v18, v20, s0, v18
	s_lshl_b32 s0, s47, 5
	s_and_b32 s90, s0, 0x60
	s_add_i32 m0, s29, 0x18000
	v_lshl_add_u64 v[8:9], v[8:9], 0, s[94:95]
	s_lshr_b32 s0, s90, 3
	global_load_lds_dwordx4 v[8:9], off
	v_lshl_add_u64 v[6:7], v[6:7], 0, s[94:95]
	s_add_i32 m0, s29, 0x1a000
	s_add_i32 s88, s29, 0x8000
	s_add_i32 s89, s29, 0xa000
	global_load_lds_dwordx4 v[6:7], off
	v_lshl_add_u64 v[2:3], v[2:3], 0, s[94:95]
	s_mov_b32 m0, s88
	s_add_u32 s12, s30, 0x40080
	global_load_lds_dwordx4 v[2:3], off
	v_lshl_add_u64 v[2:3], v[4:5], 0, s[94:95]
	s_mov_b32 m0, s89
	s_addc_u32 s13, s31, 0
	global_load_lds_dwordx4 v[2:3], off
	s_add_i32 m0, s29, 0x1c000
	v_lshl_add_u64 v[2:3], s[12:13], 0, v[0:1]
	global_load_lds_dwordx4 v[2:3], off
	v_lshl_add_u64 v[2:3], s[12:13], 0, v[166:167]
	s_add_i32 m0, s29, 0x1e000
	v_lshlrev_b32_e32 v16, 2, v16
	global_load_lds_dwordx4 v[2:3], off
	s_waitcnt vmcnt(8)
	s_barrier
	v_lshlrev_b32_e32 v2, 14, v13
	v_and_b32_e32 v2, 0xffff8000, v2
	v_lshl_add_u32 v2, v14, 11, v2
	v_and_b32_e32 v3, 1, v13
	v_lshl_or_b32 v2, v3, 6, v2
	v_lshl_add_u32 v168, v15, 1, v2
	v_lshlrev_b32_e32 v2, 14, v10
	v_and_b32_e32 v2, 0xffff8000, v2
	v_and_b32_e32 v16, 32, v16
	s_waitcnt vmcnt(6)
	v_lshl_add_u32 v2, v11, 11, v2
	v_and_b32_e32 v3, 1, v10
	v_bitop3_b32 v19, v18, v19, v16 bitop3:0xde
	v_add_lshl_u32 v17, s0, v17, 10
	s_cmp_lt_u32 s47, 4
	v_lshl_or_b32 v2, v3, 6, v2
	v_bitop3_b32 v188, v17, v18, v16 bitop3:0xf6
	s_cselect_b64 s[12:13], -1, 0
	v_mov_b32_e32 v169, v1
	v_lshl_add_u32 v170, v12, 1, v2
	v_mov_b32_e32 v171, v1
	s_mov_b32 s72, 0
	v_add_u32_e32 v189, 0, v19
	s_barrier
	s_branch .LBB0_837

; #define PG8_STAGE(bufoff, gbase, voff) do { _Pragma("unroll") for (int _i = 0; _i < 2; ++_i) \
;         __builtin_amdgcn_global_load_lds((const unsigned*)((const char*)(gbase) + (voff)[_i]), (PG8_LAS unsigned*)(lds + (bufoff) + ldsw + _i * 8192), 16, 0, 0); } while (0)
; #define PG8_WAIT_V(n) asm volatile("s_waitcnt vmcnt(" #n ")" ::: "memory")
; #define PG8_BAR __builtin_amdgcn_s_barrier()
; template <class Epi, class Sched, bool ALIGN_EPI = false, bool SP2 = false>
; __device__ __forceinline__ void gemm_phase(PG8_LAS unsigned char* lds, const Gemm g, const Sched& S, const Epi& E, int wid_in) {
;     ...
;         PG8_STAGE(PG8_SB(0, 0), cB, voffB); PG8_STAGE(PG8_SB(0, 1), cB + hstep, voffB); PG8_STAGE(PG8_SA(0, 0), cA, voffA); PG8_STAGE(PG8_SA(0, 1), cA + hstep, voffA);
;         if (wr == 1) PG8_BAR;
;         PG8_WAIT_V(2); PG8_BAR;
;         PG8_STAGE(PG8_SB(1, 0), cB + kstep, voffB); PG8_STAGE(PG8_SA(1, 0), cA + kstep, voffA); PG8_STAGE(PG8_SB(1, 1), cB + hstep + kstep, voffB);
;         PG8_WAIT_V(6); PG8_BAR;
.LBB0_866:
	s_add_u32 s8, s12, 0x3d5a0000
	s_addc_u32 s9, s13, 0
	s_add_u32 s10, s12, 0x23004200
	s_addc_u32 s11, s13, 0
	v_ashrrev_i32_e32 v17, 6, v15
	s_add_u32 s64, s12, 0x47fa0000
	v_lshlrev_b32_e32 v19, 10, v17
	s_addc_u32 s65, s13, 0
	s_lshl_b32 s80, s0, 6
	v_and_b32_e32 v18, 48, v15
	v_lshl_add_u32 v19, s0, 13, v19
	v_lshlrev_b32_e32 v20, 6, v15
	s_movk_i32 s0, 0x3c0
	v_and_or_b32 v18, v20, s0, v18
	s_lshl_b32 s0, s47, 5
	s_and_b32 s88, s0, 0x60
	s_add_i32 m0, s29, 0x18000
	v_lshl_add_u64 v[8:9], v[8:9], 0, s[94:95]
	s_lshr_b32 s0, s88, 3
	global_load_lds_dwordx4 v[8:9], off
	v_lshl_add_u64 v[6:7], v[6:7], 0, s[94:95]
	s_add_i32 m0, s29, 0x1a000
	s_add_i32 s89, s29, 0x8000
	s_add_i32 s90, s29, 0xa000
	global_load_lds_dwordx4 v[6:7], off
	v_lshl_add_u64 v[2:3], v[2:3], 0, s[94:95]
	s_mov_b32 m0, s89
	s_add_u32 s12, s30, 0x40080
	global_load_lds_dwordx4 v[2:3], off
	v_lshl_add_u64 v[2:3], v[4:5], 0, s[94:95]
	s_mov_b32 m0, s90
	s_addc_u32 s13, s31, 0
	global_load_lds_dwordx4 v[2:3], off
	s_add_i32 m0, s29, 0x1c000
	v_lshl_add_u64 v[2:3], s[12:13], 0, v[0:1]
	global_load_lds_dwordx4 v[2:3], off
	v_lshl_add_u64 v[2:3], s[12:13], 0, v[212:213]
	s_add_i32 m0, s29, 0x1e000
	v_lshlrev_b32_e32 v15, 2, v15
	global_load_lds_dwordx4 v[2:3], off
	s_waitcnt vmcnt(8)
	s_barrier
	v_lshlrev_b32_e32 v2, 14, v13
	v_and_b32_e32 v2, 0xffff8000, v2
	v_lshl_add_u32 v2, v14, 11, v2
	v_and_b32_e32 v3, 1, v13
	v_lshl_or_b32 v2, v3, 6, v2
	v_lshl_add_u32 v214, v16, 1, v2
	v_lshlrev_b32_e32 v2, 14, v10
	v_and_b32_e32 v2, 0xffff8000, v2
	v_and_b32_e32 v15, 32, v15
	s_waitcnt vmcnt(6)
	v_lshl_add_u32 v2, v11, 11, v2
	v_and_b32_e32 v3, 1, v10
	v_bitop3_b32 v19, v18, v19, v15 bitop3:0xde
	v_add_lshl_u32 v17, s0, v17, 10
	s_cmp_lt_u32 s47, 4
	v_lshl_or_b32 v2, v3, 6, v2
	v_bitop3_b32 v195, v17, v18, v15 bitop3:0xf6
	s_cselect_b64 s[12:13], -1, 0
	v_mov_b32_e32 v215, v1
	v_lshl_add_u32 v216, v12, 1, v2
	v_mov_b32_e32 v217, v1
	s_mov_b32 s72, 0
	v_add_u32_e32 v251, 0, v19
	s_brev_b32 s57, 63
	s_barrier
	s_branch .LBB0_869

; #define PG8_STAGE(bufoff, gbase, voff) do { _Pragma("unroll") for (int _i = 0; _i < 2; ++_i) \
;         __builtin_amdgcn_global_load_lds((const unsigned*)((const char*)(gbase) + (voff)[_i]), (PG8_LAS unsigned*)(lds + (bufoff) + ldsw + _i * 8192), 16, 0, 0); } while (0)
; #define PG8_WAIT_V(n) asm volatile("s_waitcnt vmcnt(" #n ")" ::: "memory")
; #define PG8_BAR __builtin_amdgcn_s_barrier()
; template <class Epi, class Sched, bool ALIGN_EPI = false, bool SP2 = false>
; __device__ __forceinline__ void gemm_phase(PG8_LAS unsigned char* lds, const Gemm g, const Sched& S, const Epi& E, int wid_in) {
;     ...
;         PG8_STAGE(PG8_SB(0, 0), cB, voffB); PG8_STAGE(PG8_SB(0, 1), cB + hstep, voffB); PG8_STAGE(PG8_SA(0, 0), cA, voffA); PG8_STAGE(PG8_SA(0, 1), cA + hstep, voffA);
;         if (wr == 1) PG8_BAR;
;         PG8_WAIT_V(2); PG8_BAR;
;         PG8_STAGE(PG8_SB(1, 0), cB + kstep, voffB); PG8_STAGE(PG8_SA(1, 0), cA + kstep, voffA); PG8_STAGE(PG8_SB(1, 1), cB + hstep + kstep, voffB);
;         PG8_WAIT_V(6); PG8_BAR;
.LBB0_1003:
	v_ashrrev_i32_e32 v17, 6, v15
	s_add_u32 s62, s8, 0x43ba0000
	v_lshlrev_b32_e32 v19, 10, v17
	s_addc_u32 s64, s9, 0
	s_lshl_b32 s65, s1, 6
	v_and_b32_e32 v18, 48, v15
	v_lshl_add_u32 v19, s1, 13, v19
	v_lshlrev_b32_e32 v20, 6, v15
	s_movk_i32 s1, 0x3c0
	v_and_or_b32 v18, v20, s1, v18
	s_lshl_b32 s1, s47, 5
	s_and_b32 s72, s1, 0x60
	s_add_i32 m0, s29, 0x18000
	v_lshl_add_u64 v[8:9], v[8:9], 0, s[94:95]
	s_lshr_b32 s1, s72, 3
	global_load_lds_dwordx4 v[8:9], off
	v_lshl_add_u64 v[6:7], v[6:7], 0, s[94:95]
	s_add_i32 m0, s29, 0x1a000
	s_add_i32 s73, s29, 0x8000
	s_add_i32 s80, s29, 0xa000
	global_load_lds_dwordx4 v[6:7], off
	v_lshl_add_u64 v[2:3], v[2:3], 0, s[94:95]
	s_mov_b32 m0, s73
	s_add_u32 s8, s30, 0x80080
	global_load_lds_dwordx4 v[2:3], off
	v_lshl_add_u64 v[2:3], v[4:5], 0, s[94:95]
	s_mov_b32 m0, s80
	s_addc_u32 s9, s31, 0
	global_load_lds_dwordx4 v[2:3], off
	s_add_i32 m0, s29, 0x1c000
	v_lshl_add_u64 v[2:3], s[8:9], 0, v[0:1]
	global_load_lds_dwordx4 v[2:3], off
	v_lshl_add_u64 v[2:3], s[8:9], 0, v[154:155]
	s_add_i32 m0, s29, 0x1e000
	v_lshlrev_b32_e32 v15, 2, v15
	global_load_lds_dwordx4 v[2:3], off
	s_waitcnt vmcnt(8)
	s_barrier
	v_lshlrev_b32_e32 v2, 15, v13
	v_and_b32_e32 v2, 0xffff0000, v2
	v_lshl_add_u32 v2, v14, 12, v2
	v_and_b32_e32 v3, 1, v13
	v_lshl_or_b32 v2, v3, 6, v2
	v_lshl_add_u32 v156, v16, 1, v2
	v_lshlrev_b32_e32 v2, 15, v10
	v_and_b32_e32 v2, 0xffff0000, v2
	v_and_b32_e32 v15, 32, v15
	s_waitcnt vmcnt(6)
	v_lshl_add_u32 v2, v11, 12, v2
	v_and_b32_e32 v3, 1, v10
	v_bitop3_b32 v19, v18, v19, v15 bitop3:0xde
	v_add_lshl_u32 v17, s1, v17, 10
	s_cmp_lt_u32 s47, 4
	v_lshl_or_b32 v2, v3, 6, v2
	v_bitop3_b32 v176, v17, v18, v15 bitop3:0xf6
	s_cselect_b64 s[14:15], -1, 0
	v_mov_b32_e32 v157, v1
	v_lshl_add_u32 v158, v12, 1, v2
	v_mov_b32_e32 v159, v1
	s_mov_b32 s88, 0
	v_add_u32_e32 v177, 0, v19
	s_brev_b32 s42, 63
	s_mov_b32 s43, 0xfc010000
	s_mov_b32 s57, 0xfc011000
	s_barrier
	s_branch .LBB0_1006

; #define PG8_STAGE(bufoff, gbase, voff) do { _Pragma("unroll") for (int _i = 0; _i < 2; ++_i) \
;         __builtin_amdgcn_global_load_lds((const unsigned*)((const char*)(gbase) + (voff)[_i]), (PG8_LAS unsigned*)(lds + (bufoff) + ldsw + _i * 8192), 16, 0, 0); } while (0)
; #define PG8_WAIT_V(n) asm volatile("s_waitcnt vmcnt(" #n ")" ::: "memory")
; #define PG8_BAR __builtin_amdgcn_s_barrier()
; template <class Epi, class Sched, bool ALIGN_EPI = false, bool SP2 = false>
; __device__ __forceinline__ void gemm_phase(PG8_LAS unsigned char* lds, const Gemm g, const Sched& S, const Epi& E, int wid_in) {
;     ...
;         PG8_STAGE(PG8_SB(0, 0), cB, voffB); PG8_STAGE(PG8_SB(0, 1), cB + hstep, voffB); PG8_STAGE(PG8_SA(0, 0), cA, voffA); PG8_STAGE(PG8_SA(0, 1), cA + hstep, voffA);
;         if (wr == 1) PG8_BAR;
;         PG8_WAIT_V(2); PG8_BAR;
;         PG8_STAGE(PG8_SB(1, 0), cB + kstep, voffB); PG8_STAGE(PG8_SA(1, 0), cA + kstep, voffA); PG8_STAGE(PG8_SB(1, 1), cB + hstep + kstep, voffB);
;         PG8_WAIT_V(6); PG8_BAR;
.LBB0_1147:
	s_add_u32 s12, s8, 0x23000000
	v_and_b32_e32 v18, 48, v16
	v_lshlrev_b32_e32 v20, 6, v16
	s_movk_i32 s8, 0x3c0
	s_addc_u32 s13, s9, 0
	v_and_or_b32 v18, v20, s8, v18
	s_lshl_b32 s8, s47, 5
	s_and_b32 s39, s8, 0x60
	s_add_i32 m0, s34, 0x18000
	v_lshl_add_u64 v[8:9], v[8:9], 0, s[94:95]
	s_lshl_b32 s38, s14, 6
	v_ashrrev_i32_e32 v17, 6, v16
	s_lshr_b32 s8, s39, 3
	global_load_lds_dwordx4 v[8:9], off
	v_lshl_add_u64 v[6:7], v[6:7], 0, s[94:95]
	s_add_i32 m0, s34, 0x1a000
	s_add_i32 s48, s34, 0x8000
	s_add_i32 s52, s34, 0xa000
	v_lshlrev_b32_e32 v19, 10, v17
	v_add_lshl_u32 v17, s8, v17, 10
	global_load_lds_dwordx4 v[6:7], off
	v_lshl_add_u64 v[2:3], v[2:3], 0, s[94:95]
	s_mov_b32 m0, s48
	s_add_u32 s8, s26, 0x80080
	global_load_lds_dwordx4 v[2:3], off
	v_lshl_add_u64 v[2:3], v[4:5], 0, s[94:95]
	s_mov_b32 m0, s52
	s_addc_u32 s9, s27, 0
	global_load_lds_dwordx4 v[2:3], off
	s_add_i32 m0, s34, 0x1c000
	v_lshl_add_u64 v[2:3], s[8:9], 0, v[0:1]
	global_load_lds_dwordx4 v[2:3], off
	v_lshl_add_u64 v[2:3], s[8:9], 0, v[130:131]
	s_add_i32 m0, s34, 0x1e000
	v_lshlrev_b32_e32 v16, 2, v16
	global_load_lds_dwordx4 v[2:3], off
	s_waitcnt vmcnt(8)
	s_barrier
	v_lshlrev_b32_e32 v2, 15, v10
	v_and_b32_e32 v2, 0xffff0000, v2
	v_lshl_add_u32 v2, v11, 12, v2
	v_and_b32_e32 v3, 1, v10
	v_lshl_or_b32 v2, v3, 6, v2
	v_lshl_add_u32 v136, v12, 1, v2
	v_lshlrev_b32_e32 v2, 15, v13
	v_and_b32_e32 v2, 0xffff0000, v2
	v_lshl_add_u32 v19, s14, 13, v19
	v_and_b32_e32 v16, 32, v16
	s_waitcnt vmcnt(6)
	v_lshl_add_u32 v2, v14, 12, v2
	v_and_b32_e32 v3, 1, v13
	v_bitop3_b32 v19, v18, v19, v16 bitop3:0xde
	s_cmp_lt_u32 s47, 4
	v_lshl_or_b32 v2, v3, 6, v2
	v_readlane_b32 s8, v255, 19
	v_bitop3_b32 v142, v17, v18, v16 bitop3:0xf6
	s_cselect_b64 s[14:15], -1, 0
	v_mov_b32_e32 v137, v1
	v_lshl_add_u32 v138, v15, 1, v2
	v_mov_b32_e32 v139, v1
	s_mov_b32 s53, 0
	v_add_u32_e32 v143, 0, v19
	v_readlane_b32 s62, v255, 16
	s_mov_b32 s61, s8
	s_barrier
	v_readlane_b32 s9, v255, 20
	s_branch .LBB0_1150

; #define PG8_STAGE(bufoff, gbase, voff) do { _Pragma("unroll") for (int _i = 0; _i < 2; ++_i) \
;         __builtin_amdgcn_global_load_lds((const unsigned*)((const char*)(gbase) + (voff)[_i]), (PG8_LAS unsigned*)(lds + (bufoff) + ldsw + _i * 8192), 16, 0, 0); } while (0)
; #define PG8_WAIT_V(n) asm volatile("s_waitcnt vmcnt(" #n ")" ::: "memory")
; #define PG8_BAR __builtin_amdgcn_s_barrier()
; template <class Epi, class Sched, bool ALIGN_EPI = false, bool SP2 = false>
; __device__ __forceinline__ void gemm_phase(PG8_LAS unsigned char* lds, const Gemm g, const Sched& S, const Epi& E, int wid_in) {
;     ...
;         PG8_STAGE(PG8_SB(0, 0), cB, voffB); PG8_STAGE(PG8_SB(0, 1), cB + hstep, voffB); PG8_STAGE(PG8_SA(0, 0), cA, voffA); PG8_STAGE(PG8_SA(0, 1), cA + hstep, voffA);
;         if (wr == 1) PG8_BAR;
;         PG8_WAIT_V(2); PG8_BAR;
;         PG8_STAGE(PG8_SB(1, 0), cB + kstep, voffB); PG8_STAGE(PG8_SA(1, 0), cA + kstep, voffA); PG8_STAGE(PG8_SB(1, 1), cB + hstep + kstep, voffB);
;         PG8_WAIT_V(6); PG8_BAR;
.LBB0_1215:
	s_add_u32 s6, s14, 0x3d5a0000
	s_addc_u32 s7, s15, 0
	s_cmp_eq_u32 s12, 3
	v_ashrrev_i32_e32 v17, 6, v15
	s_cselect_b32 s13, s7, s9
	s_cselect_b32 s12, s6, s8
	s_add_u32 s62, s14, 0x43ba0000
	v_lshlrev_b32_e32 v19, 10, v17
	s_addc_u32 s64, s15, 0
	s_lshl_b32 s65, s1, 6
	v_and_b32_e32 v18, 48, v15
	v_lshl_add_u32 v19, s1, 13, v19
	v_lshlrev_b32_e32 v20, 6, v15
	s_movk_i32 s1, 0x3c0
	v_and_or_b32 v18, v20, s1, v18
	s_lshl_b32 s1, s47, 5
	s_and_b32 s72, s1, 0x60
	s_add_i32 m0, s29, 0x18000
	v_lshl_add_u64 v[8:9], v[8:9], 0, s[94:95]
	s_lshr_b32 s1, s72, 3
	global_load_lds_dwordx4 v[8:9], off
	v_lshl_add_u64 v[6:7], v[6:7], 0, s[94:95]
	s_add_i32 m0, s29, 0x1a000
	s_add_i32 s73, s29, 0x8000
	s_add_i32 s80, s29, 0xa000
	global_load_lds_dwordx4 v[6:7], off
	v_lshl_add_u64 v[2:3], v[2:3], 0, s[94:95]
	s_mov_b32 m0, s73
	s_add_u32 s6, s30, 0x200080
	global_load_lds_dwordx4 v[2:3], off
	v_lshl_add_u64 v[2:3], v[4:5], 0, s[94:95]
	s_mov_b32 m0, s80
	s_addc_u32 s7, s31, 0
	global_load_lds_dwordx4 v[2:3], off
	s_add_i32 m0, s29, 0x1c000
	v_lshl_add_u64 v[2:3], s[6:7], 0, v[0:1]
	global_load_lds_dwordx4 v[2:3], off
	v_lshl_add_u64 v[2:3], s[6:7], 0, v[154:155]
	s_add_i32 m0, s29, 0x1e000
	v_lshlrev_b32_e32 v15, 2, v15
	global_load_lds_dwordx4 v[2:3], off
	s_waitcnt vmcnt(8)
	s_barrier
	v_lshlrev_b32_e32 v2, 17, v13
	v_and_b32_e32 v2, 0xfffc0000, v2
	v_lshl_add_u32 v2, v14, 14, v2
	v_and_b32_e32 v3, 1, v13
	v_lshl_or_b32 v2, v3, 6, v2
	v_lshl_add_u32 v156, v16, 1, v2
	v_lshlrev_b32_e32 v2, 17, v10
	v_and_b32_e32 v2, 0xfffc0000, v2
	v_and_b32_e32 v15, 32, v15
	s_waitcnt vmcnt(6)
	v_lshl_add_u32 v2, v11, 14, v2
	v_and_b32_e32 v3, 1, v10
	v_bitop3_b32 v19, v18, v19, v15 bitop3:0xde
	v_add_lshl_u32 v17, s1, v17, 10
	s_cmp_lt_u32 s47, 4
	v_lshl_or_b32 v2, v3, 6, v2
	v_bitop3_b32 v176, v17, v18, v15 bitop3:0xf6
	s_cselect_b64 s[14:15], -1, 0
	v_mov_b32_e32 v157, v1
	v_lshl_add_u32 v158, v12, 1, v2
	v_mov_b32_e32 v159, v1
	s_mov_b32 s88, 0
	v_add_u32_e32 v177, 0, v19
	s_brev_b32 s42, 63
	s_mov_b32 s43, 0xfc010000
	s_mov_b32 s57, 0xfc011000
	s_barrier
	s_branch .LBB0_1218
